# attention loops: cross-half row max via v_permlane32_swap instead of ds_bpermute; diff-latent loop: first K reads hoisted above prefetch address math, exp-section temp pair alternated
# speedup vs baseline: 1.0099x; 1.0059x over previous
.LBB0_316:
	s_bitcmp1_b32 s1, 0
	s_cselect_b32 s1, 0x4800, 0
	v_or_b32_e32 v34, s1, v0
	v_add_u32_e32 v110, v34, v115
	ds_read_b128 v[34:37], v110
	ds_read_b128 v[38:41], v110 offset:32
	s_mov_b32 s5, 0xff800000
	s_waitcnt lgkmcnt(1)
	v_mfma_f32_32x32x16_bf16 v[50:65], v[34:37], v[66:69], 0
	ds_read_b128 v[34:37], v110 offset:64
	ds_read_b128 v[120:123], v110 offset:4640
	s_waitcnt lgkmcnt(2)
	v_mfma_f32_32x32x16_bf16 v[50:65], v[38:41], v[70:73], v[50:65]
	s_waitcnt lgkmcnt(1)
	v_mfma_f32_32x32x16_bf16 v[50:65], v[34:37], v[74:77], v[50:65]
	ds_read_b128 v[34:37], v110 offset:96
	s_waitcnt lgkmcnt(0)
	v_mfma_f32_32x32x16_bf16 v[50:65], v[34:37], v[78:81], v[50:65]
	ds_read_b128 v[34:37], v110 offset:4608
	s_waitcnt lgkmcnt(0)
	v_mfma_f32_32x32x16_bf16 v[34:49], v[34:37], v[66:69], 0
	v_mfma_f32_32x32x16_bf16 v[34:49], v[120:123], v[70:73], v[34:49]
	ds_read_b128 v[120:123], v110 offset:4672
	s_waitcnt lgkmcnt(0)
	v_mfma_f32_32x32x16_bf16 v[34:49], v[120:123], v[74:77], v[34:49]
	ds_read_b128 v[120:123], v110 offset:4704
	s_nop 3
	v_max3_f32 v110, v50, s5, v51
	v_max3_f32 v110, v110, v52, v53
	v_max3_f32 v110, v110, v54, v55
	v_max3_f32 v110, v110, v56, v57
	v_max3_f32 v110, v110, v58, v59
	v_max3_f32 v110, v110, v60, v61
	s_waitcnt lgkmcnt(0)
	v_mfma_f32_32x32x16_bf16 v[34:49], v[120:123], v[78:81], v[34:49]
	v_max3_f32 v110, v110, v62, v63
	v_max3_f32 v110, v110, v64, v65
	s_nop 9
	v_max3_f32 v110, v110, v34, v35
	v_max3_f32 v110, v110, v36, v37
	v_max3_f32 v110, v110, v38, v39
	v_max3_f32 v110, v110, v40, v41
	v_max3_f32 v110, v110, v42, v43
	v_max3_f32 v110, v110, v44, v45
	v_max3_f32 v110, v110, v46, v47
	v_max3_f32 v110, v110, v48, v49
	v_mul_f32_e32 v110, 0x3e38aa3b, v110
	v_mov_b32_e32 v112, v110
	s_nop 1
	v_permlane32_swap_b32_e32 v112, v110
	s_nop 0
	s_waitcnt lgkmcnt(0)
	v_max3_f32 v110, v118, v110, v112
	v_sub_f32_e32 v112, v118, v110
	v_exp_f32_e32 v112, v112
	v_cmp_neq_f32_e32 vcc, v110, v118
	s_cbranch_vccz .LBB0_318
	v_pk_mul_f32 v[32:33], v[32:33], v[112:113] op_sel_hi:[1,0]
	v_pk_mul_f32 v[30:31], v[30:31], v[112:113] op_sel_hi:[1,0]
	v_pk_mul_f32 v[28:29], v[28:29], v[112:113] op_sel_hi:[1,0]
	v_pk_mul_f32 v[26:27], v[26:27], v[112:113] op_sel_hi:[1,0]
	v_pk_mul_f32 v[24:25], v[24:25], v[112:113] op_sel_hi:[1,0]
	v_pk_mul_f32 v[22:23], v[22:23], v[112:113] op_sel_hi:[1,0]
	v_pk_mul_f32 v[20:21], v[20:21], v[112:113] op_sel_hi:[1,0]
	v_pk_mul_f32 v[18:19], v[18:19], v[112:113] op_sel_hi:[1,0]
	v_pk_mul_f32 v[16:17], v[16:17], v[112:113] op_sel_hi:[1,0]
	v_pk_mul_f32 v[14:15], v[14:15], v[112:113] op_sel_hi:[1,0]
	v_pk_mul_f32 v[12:13], v[12:13], v[112:113] op_sel_hi:[1,0]
	v_pk_mul_f32 v[10:11], v[10:11], v[112:113] op_sel_hi:[1,0]
	v_pk_mul_f32 v[8:9], v[8:9], v[112:113] op_sel_hi:[1,0]
	v_pk_mul_f32 v[6:7], v[6:7], v[112:113] op_sel_hi:[1,0]
	v_pk_mul_f32 v[4:5], v[4:5], v[112:113] op_sel_hi:[1,0]
	v_pk_mul_f32 v[2:3], v[2:3], v[112:113] op_sel_hi:[1,0]

.LBB0_326:
	s_bitcmp1_b32 s1, 0
	s_cselect_b32 s1, 0x4800, 0
	v_or_b32_e32 v66, s1, v0
	v_add_u32_e32 v210, v66, v234
	ds_read_b128 v[66:69], v210
	ds_read_b128 v[70:73], v210 offset:32
	s_mov_b32 s5, 0xff800000
	s_waitcnt lgkmcnt(1)
	v_mfma_f32_32x32x16_bf16 v[82:97], v[66:69], v[98:101], 0
	ds_read_b128 v[66:69], v210 offset:4608
	ds_read_b128 v[132:135], v210 offset:4640
	s_waitcnt lgkmcnt(2)
	v_mfma_f32_32x32x16_bf16 v[82:97], v[70:73], v[102:105], v[82:97]
	s_waitcnt lgkmcnt(1)
	v_mfma_f32_32x32x16_bf16 v[66:81], v[66:69], v[98:101], 0
	s_nop 9
	v_max3_f32 v131, v82, s5, v83
	v_max3_f32 v131, v131, v84, v85
	v_max3_f32 v131, v131, v86, v87
	v_max3_f32 v131, v131, v88, v89
	v_max3_f32 v131, v131, v90, v91
	v_max3_f32 v131, v131, v92, v93
	v_max3_f32 v131, v131, v94, v95
	s_waitcnt lgkmcnt(0)
	v_mfma_f32_32x32x16_bf16 v[66:81], v[132:135], v[102:105], v[66:81]
	v_max3_f32 v131, v131, v96, v97
	s_nop 10
	v_max3_f32 v131, v131, v66, v67
	v_max3_f32 v131, v131, v68, v69
	v_max3_f32 v131, v131, v70, v71
	v_max3_f32 v131, v131, v72, v73
	v_max3_f32 v131, v131, v74, v75
	v_max3_f32 v131, v131, v76, v77
	v_max3_f32 v131, v131, v78, v79
	v_max3_f32 v131, v131, v80, v81
	v_mul_f32_e32 v131, 0x3e8293ee, v131
	v_mov_b32_e32 v132, v131
	s_nop 1
	v_permlane32_swap_b32_e32 v132, v131
	s_nop 0
	s_waitcnt lgkmcnt(0)
	v_max3_f32 v174, v130, v131, v132
	v_sub_f32_e32 v131, v130, v174
	v_exp_f32_e32 v176, v131
	v_cmp_neq_f32_e32 vcc, v174, v130
	s_cbranch_vccz .LBB0_328
	v_pk_mul_f32 v[48:49], v[48:49], v[176:177] op_sel_hi:[1,0]
	v_pk_mul_f32 v[46:47], v[46:47], v[176:177] op_sel_hi:[1,0]
	v_pk_mul_f32 v[44:45], v[44:45], v[176:177] op_sel_hi:[1,0]
	v_pk_mul_f32 v[42:43], v[42:43], v[176:177] op_sel_hi:[1,0]
	v_pk_mul_f32 v[40:41], v[40:41], v[176:177] op_sel_hi:[1,0]
	v_pk_mul_f32 v[38:39], v[38:39], v[176:177] op_sel_hi:[1,0]
	v_pk_mul_f32 v[36:37], v[36:37], v[176:177] op_sel_hi:[1,0]
	v_pk_mul_f32 v[34:35], v[34:35], v[176:177] op_sel_hi:[1,0]
	v_pk_mul_f32 v[32:33], v[32:33], v[176:177] op_sel_hi:[1,0]
	v_pk_mul_f32 v[30:31], v[30:31], v[176:177] op_sel_hi:[1,0]
	v_pk_mul_f32 v[28:29], v[28:29], v[176:177] op_sel_hi:[1,0]
	v_pk_mul_f32 v[26:27], v[26:27], v[176:177] op_sel_hi:[1,0]
	v_pk_mul_f32 v[24:25], v[24:25], v[176:177] op_sel_hi:[1,0]
	v_pk_mul_f32 v[22:23], v[22:23], v[176:177] op_sel_hi:[1,0]
	v_pk_mul_f32 v[20:21], v[20:21], v[176:177] op_sel_hi:[1,0]
	v_pk_mul_f32 v[18:19], v[18:19], v[176:177] op_sel_hi:[1,0]
.LBB0_328:
	v_pk_fma_f32 v[66:67], v[66:67], s[58:59], v[174:175] op_sel_hi:[1,0,0] neg_lo:[0,0,1] neg_hi:[0,0,1]
	v_pk_fma_f32 v[82:83], v[82:83], s[58:59], v[174:175] op_sel_hi:[1,0,0] neg_lo:[0,0,1] neg_hi:[0,0,1]
	v_exp_f32_e32 v198, v66
	v_exp_f32_e32 v199, v67
	v_pk_fma_f32 v[66:67], v[68:69], s[58:59], v[174:175] op_sel_hi:[1,0,0] neg_lo:[0,0,1] neg_hi:[0,0,1]
	v_exp_f32_e32 v180, v82
	v_exp_f32_e32 v204, v66
	v_exp_f32_e32 v205, v67
	v_pk_fma_f32 v[66:67], v[70:71], s[58:59], v[174:175] op_sel_hi:[1,0,0] neg_lo:[0,0,1] neg_hi:[0,0,1]
	v_add3_u32 v70, s1, v177, v234
	v_add_u32_e32 v71, 0x2000, v70
	v_add_u32_e32 v70, 0x3000, v70
	ds_read2_b64 v[134:137], v71 offset0:128 offset1:130
	ds_read2_b64 v[130:133], v71 offset0:132 offset1:134
	ds_read2_b64 v[138:141], v70 offset0:192 offset1:194
	v_exp_f32_e32 v181, v83
	v_pk_fma_f32 v[82:83], v[84:85], s[58:59], v[174:175] op_sel_hi:[1,0,0] neg_lo:[0,0,1] neg_hi:[0,0,1]
	v_exp_f32_e32 v208, v66
	v_exp_f32_e32 v178, v82
	v_exp_f32_e32 v179, v83
	v_pk_fma_f32 v[82:83], v[86:87], s[58:59], v[174:175] op_sel_hi:[1,0,0] neg_lo:[0,0,1] neg_hi:[0,0,1]
	v_exp_f32_e32 v209, v67
	v_exp_f32_e32 v182, v82
	v_exp_f32_e32 v183, v83
	v_pk_fma_f32 v[82:83], v[88:89], s[58:59], v[174:175] op_sel_hi:[1,0,0] neg_lo:[0,0,1] neg_hi:[0,0,1]
	v_pk_fma_f32 v[66:67], v[72:73], s[58:59], v[174:175] op_sel_hi:[1,0,0] neg_lo:[0,0,1] neg_hi:[0,0,1]
	v_exp_f32_e32 v184, v82
	v_exp_f32_e32 v185, v83
	v_exp_f32_e32 v190, v66
	v_exp_f32_e32 v191, v67
	v_pk_fma_f32 v[66:67], v[74:75], s[58:59], v[174:175] op_sel_hi:[1,0,0] neg_lo:[0,0,1] neg_hi:[0,0,1]
	v_pk_fma_f32 v[82:83], v[90:91], s[58:59], v[174:175] op_sel_hi:[1,0,0] neg_lo:[0,0,1] neg_hi:[0,0,1]
	v_exp_f32_e32 v192, v66
	v_exp_f32_e32 v193, v67
	v_pk_fma_f32 v[66:67], v[76:77], s[58:59], v[174:175] op_sel_hi:[1,0,0] neg_lo:[0,0,1] neg_hi:[0,0,1]
	v_cvt_pk_bf16_f32 v68, v182, v183
	v_exp_f32_e32 v196, v66
	v_exp_f32_e32 v197, v67
	v_pk_fma_f32 v[66:67], v[78:79], s[58:59], v[174:175] op_sel_hi:[1,0,0] neg_lo:[0,0,1] neg_hi:[0,0,1]
	v_cvt_pk_bf16_f32 v69, v184, v185
	v_exp_f32_e32 v202, v66
	v_exp_f32_e32 v203, v67
	v_pk_fma_f32 v[66:67], v[80:81], s[58:59], v[174:175] op_sel_hi:[1,0,0] neg_lo:[0,0,1] neg_hi:[0,0,1]
	ds_read2_b64 v[142:145], v70 offset0:196 offset1:198
	v_exp_f32_e32 v206, v66
	v_exp_f32_e32 v207, v67
	v_cvt_pk_bf16_f32 v66, v180, v181
	v_cvt_pk_bf16_f32 v67, v178, v179
	v_exp_f32_e32 v186, v82
	v_exp_f32_e32 v187, v83
	v_pk_fma_f32 v[82:83], v[92:93], s[58:59], v[174:175] op_sel_hi:[1,0,0] neg_lo:[0,0,1] neg_hi:[0,0,1]
	s_waitcnt lgkmcnt(3)
	v_mfma_f32_32x32x16_bf16 v[34:49], v[134:137], v[66:69], v[34:49]
	v_exp_f32_e32 v188, v82
	v_exp_f32_e32 v189, v83
	v_pk_fma_f32 v[82:83], v[94:95], s[58:59], v[174:175] op_sel_hi:[1,0,0] neg_lo:[0,0,1] neg_hi:[0,0,1]
	ds_read2_b64 v[146:149], v71 offset0:136 offset1:138
	v_exp_f32_e32 v194, v82
	v_exp_f32_e32 v195, v83
	v_pk_fma_f32 v[82:83], v[96:97], s[58:59], v[174:175] op_sel_hi:[1,0,0] neg_lo:[0,0,1] neg_hi:[0,0,1]
	s_waitcnt lgkmcnt(2)
	v_mfma_f32_32x32x16_bf16 v[18:33], v[138:141], v[66:69], v[18:33]
	v_exp_f32_e32 v200, v82
	v_exp_f32_e32 v201, v83
	v_cvt_pk_bf16_f32 v66, v186, v187
	v_cvt_pk_bf16_f32 v67, v188, v189
	v_cvt_pk_bf16_f32 v68, v194, v195
	v_cvt_pk_bf16_f32 v69, v200, v201
	ds_read2_b64 v[150:153], v70 offset0:200 offset1:202
	ds_read2_b64 v[154:157], v71 offset0:140 offset1:142
	v_mfma_f32_32x32x16_bf16 v[34:49], v[130:133], v[66:69], v[34:49]
	ds_read2_b64 v[158:161], v70 offset0:204 offset1:206
	s_mov_b32 s1, 0xff800000
	s_waitcnt lgkmcnt(4)
	v_mfma_f32_32x32x16_bf16 v[18:33], v[142:145], v[66:69], v[18:33]
	v_cvt_pk_bf16_f32 v66, v198, v199
	v_cvt_pk_bf16_f32 v67, v204, v205
	v_cvt_pk_bf16_f32 v68, v208, v209
	v_cvt_pk_bf16_f32 v69, v190, v191
	s_waitcnt lgkmcnt(3)
	s_nop 0
	v_mfma_f32_32x32x16_bf16 v[34:49], v[146:149], v[66:69], v[34:49]
	s_waitcnt lgkmcnt(2)
	v_mfma_f32_32x32x16_bf16 v[18:33], v[150:153], v[66:69], v[18:33]
	v_cvt_pk_bf16_f32 v66, v192, v193
	v_cvt_pk_bf16_f32 v67, v196, v197
	v_cvt_pk_bf16_f32 v68, v202, v203
	v_cvt_pk_bf16_f32 v69, v206, v207
	s_waitcnt lgkmcnt(1)
	s_nop 0
	v_mfma_f32_32x32x16_bf16 v[34:49], v[154:157], v[66:69], v[34:49]
	s_waitcnt lgkmcnt(0)
	v_mfma_f32_32x32x16_bf16 v[18:33], v[158:161], v[66:69], v[18:33]
	ds_read_b128 v[66:69], v210 offset:64
	ds_read_b128 v[70:73], v210 offset:96
	ds_read_b128 v[240:243], v210 offset:4704
	s_waitcnt lgkmcnt(2)
	v_mfma_f32_32x32x16_bf16 v[82:97], v[66:69], v[106:109], 0
	ds_read_b128 v[66:69], v210 offset:4672
	s_waitcnt lgkmcnt(2)
	v_mfma_f32_32x32x16_bf16 v[82:97], v[70:73], v[110:113], v[82:97]
	s_waitcnt lgkmcnt(0)
	v_mfma_f32_32x32x16_bf16 v[66:81], v[66:69], v[106:109], 0
	s_nop 9
	v_max3_f32 v210, v82, s1, v83
	v_max3_f32 v210, v210, v84, v85
	v_max3_f32 v210, v210, v86, v87
	v_max3_f32 v210, v210, v88, v89
	v_max3_f32 v210, v210, v90, v91
	v_max3_f32 v210, v210, v92, v93
	v_max3_f32 v210, v210, v94, v95
	v_mfma_f32_32x32x16_bf16 v[66:81], v[240:243], v[110:113], v[66:81]
	v_max3_f32 v210, v210, v96, v97
	s_nop 10
	v_max3_f32 v210, v210, v66, v67
	v_max3_f32 v210, v210, v68, v69
	v_max3_f32 v210, v210, v70, v71
	v_max3_f32 v210, v210, v72, v73
	v_max3_f32 v210, v210, v74, v75
	v_max3_f32 v210, v210, v76, v77
	v_max3_f32 v210, v210, v78, v79
	v_max3_f32 v210, v210, v80, v81
	v_mul_f32_e32 v210, 0x3e8293ee, v210
	v_mov_b32_e32 v211, v210
	s_nop 1
	v_permlane32_swap_b32_e32 v211, v210
	s_nop 0
	s_waitcnt lgkmcnt(0)
	v_max3_f32 v210, v239, v210, v211
	v_sub_f32_e32 v211, v239, v210
	v_exp_f32_e32 v212, v211
	v_cmp_neq_f32_e32 vcc, v210, v239
	s_cbranch_vccz .LBB0_330
	v_pk_mul_f32 v[64:65], v[64:65], v[212:213] op_sel_hi:[1,0]
	v_pk_mul_f32 v[62:63], v[62:63], v[212:213] op_sel_hi:[1,0]
	v_pk_mul_f32 v[60:61], v[60:61], v[212:213] op_sel_hi:[1,0]
	v_pk_mul_f32 v[58:59], v[58:59], v[212:213] op_sel_hi:[1,0]
	v_pk_mul_f32 v[56:57], v[56:57], v[212:213] op_sel_hi:[1,0]
	v_pk_mul_f32 v[54:55], v[54:55], v[212:213] op_sel_hi:[1,0]
	v_pk_mul_f32 v[52:53], v[52:53], v[212:213] op_sel_hi:[1,0]
	v_pk_mul_f32 v[50:51], v[50:51], v[212:213] op_sel_hi:[1,0]
	v_pk_mul_f32 v[16:17], v[16:17], v[212:213] op_sel_hi:[1,0]
	v_pk_mul_f32 v[14:15], v[14:15], v[212:213] op_sel_hi:[1,0]
	v_pk_mul_f32 v[12:13], v[12:13], v[212:213] op_sel_hi:[1,0]
	v_pk_mul_f32 v[10:11], v[10:11], v[212:213] op_sel_hi:[1,0]
	v_pk_mul_f32 v[8:9], v[8:9], v[212:213] op_sel_hi:[1,0]
	v_pk_mul_f32 v[6:7], v[6:7], v[212:213] op_sel_hi:[1,0]
	v_pk_mul_f32 v[4:5], v[4:5], v[212:213] op_sel_hi:[1,0]
	v_pk_mul_f32 v[2:3], v[2:3], v[212:213] op_sel_hi:[1,0]

.Lna_nobias:
	s_mov_b32 s40, 0xff800000
	v_max3_f32 v34, v50, s40, v51
	v_max3_f32 v34, v34, v52, v53
	v_max3_f32 v34, v34, v54, v55
	v_max3_f32 v34, v34, v56, v57
	v_max3_f32 v34, v34, v58, v59
	v_max3_f32 v34, v34, v60, v61
	v_max3_f32 v34, v34, v62, v63
	v_max3_f32 v34, v34, v64, v65
	v_max3_f32 v34, v34, v119, v120
	v_max3_f32 v34, v34, v36, v37
	v_max3_f32 v34, v34, v38, v39
	v_max3_f32 v34, v34, v40, v41
	v_max3_f32 v34, v34, v42, v43
	v_max3_f32 v34, v34, v44, v45
	v_max3_f32 v34, v34, v46, v47
	v_max3_f32 v34, v34, v48, v49
	v_mov_b32_e32 v35, v34
	s_nop 1
	v_permlane32_swap_b32_e32 v35, v34
	s_nop 0
	v_readlane_b32 s62, v254, 41
	v_readlane_b32 s63, v254, 42
	s_waitcnt lgkmcnt(0)
	v_max3_f32 v35, v118, v34, v35
	v_sub_f32_e32 v34, v118, v35
	v_exp_f32_e32 v34, v34
	v_cmp_neq_f32_e32 vcc, v35, v118
	s_cbranch_vccz .LBB0_389
	v_pk_mul_f32 v[32:33], v[32:33], v[34:35] op_sel_hi:[1,0]
	v_pk_mul_f32 v[30:31], v[30:31], v[34:35] op_sel_hi:[1,0]
	v_pk_mul_f32 v[28:29], v[28:29], v[34:35] op_sel_hi:[1,0]
	v_pk_mul_f32 v[26:27], v[26:27], v[34:35] op_sel_hi:[1,0]
	v_pk_mul_f32 v[24:25], v[24:25], v[34:35] op_sel_hi:[1,0]
	v_pk_mul_f32 v[22:23], v[22:23], v[34:35] op_sel_hi:[1,0]
	v_pk_mul_f32 v[20:21], v[20:21], v[34:35] op_sel_hi:[1,0]
	v_pk_mul_f32 v[18:19], v[18:19], v[34:35] op_sel_hi:[1,0]
	v_pk_mul_f32 v[16:17], v[16:17], v[34:35] op_sel_hi:[1,0]
	v_pk_mul_f32 v[14:15], v[14:15], v[34:35] op_sel_hi:[1,0]
	v_pk_mul_f32 v[12:13], v[12:13], v[34:35] op_sel_hi:[1,0]
	v_pk_mul_f32 v[10:11], v[10:11], v[34:35] op_sel_hi:[1,0]
	v_pk_mul_f32 v[8:9], v[8:9], v[34:35] op_sel_hi:[1,0]
	v_pk_mul_f32 v[6:7], v[6:7], v[34:35] op_sel_hi:[1,0]
	v_pk_mul_f32 v[4:5], v[4:5], v[34:35] op_sel_hi:[1,0]
	v_pk_mul_f32 v[2:3], v[2:3], v[34:35] op_sel_hi:[1,0]

.LBB0_427:
	s_bitcmp1_b32 s18, 0
	s_cselect_b32 s98, 0x4800, 0
	v_or_b32_e32 v210, s98, v166
	v_add_u32_e32 v210, v210, v171
	ds_read_b128 v[4:7], v210
	ds_read_b128 v[8:11], v210 offset:32
	s_cmpk_gt_u32 s18, 0x41
	s_cbranch_scc1 .LBB0_431
	s_mov_b64 s[8:9], 0x100
	s_cmp_lt_u32 s18, 2
	s_mov_b64 s[4:5], s[0:1]
	s_mov_b64 s[6:7], s[2:3]
	s_cbranch_scc1 .LBB0_430
	s_lshl_b64 s[4:5], s[56:57], 7
	s_add_u32 s6, s15, s4
	s_addc_u32 s7, s16, s5
	s_lshl_b64 s[4:5], s[56:57], 1
	s_add_u32 s4, s13, s4
	s_addc_u32 s5, s14, s5
	s_mov_b64 s[8:9], 0x1000
.LBB0_430:
	v_lshl_add_u64 v[80:81], v[168:169], 1, s[6:7]
	global_load_dwordx4 v[128:131], v[80:81], off
	v_mad_i64_i32 v[80:81], s[20:21], s8, v170, 0
	v_lshl_add_u64 v[80:81], v[80:81], 1, s[4:5]
	v_lshlrev_b32_e32 v0, 1, v164
	v_lshl_add_u64 v[80:81], v[80:81], 0, v[0:1]
	global_load_dwordx4 v[132:135], v[80:81], off
	v_lshl_add_u64 v[80:81], v[174:175], 1, s[6:7]
	global_load_dwordx4 v[136:139], v[80:81], off
	v_mad_i64_i32 v[80:81], s[6:7], s8, v176, 0
	v_lshl_add_u64 v[80:81], v[80:81], 1, s[4:5]
	v_lshl_add_u64 v[80:81], v[80:81], 0, v[0:1]
	global_load_dwordx4 v[140:143], v[80:81], off
.LBB0_431:
	s_bitcmp1_b32 s18, 0
	s_cselect_b32 s4, 0x4800, 0
	v_or_b32_e32 v0, s4, v166
	v_add_u32_e32 v210, v0, v171
	s_mov_b32 s5, 0xff800000
	s_waitcnt lgkmcnt(1)
	v_mfma_f32_32x32x16_bf16 v[96:111], v[4:7], v[112:115], 0
	ds_read_b128 v[4:7], v210 offset:4608
	s_waitcnt lgkmcnt(1)
	v_mfma_f32_32x32x16_bf16 v[96:111], v[8:11], v[116:119], v[96:111]
	s_waitcnt lgkmcnt(0)
	v_mfma_f32_32x32x16_bf16 v[80:95], v[4:7], v[112:115], 0
	ds_read_b128 v[4:7], v210 offset:4640
	ds_read_b128 v[244:247], v210 offset:64
	ds_read_b128 v[214:217], v210 offset:96
	ds_read_b128 v[228:231], v210 offset:4672
	v_add3_u32 v248, s4, v235, v171
	v_add_u32_e32 v249, 0x3000, v248
	v_add_u32_e32 v248, 0x2000, v248
	ds_read2_b64 v[144:147], v249 offset0:196 offset1:198
	ds_read2_b64 v[148:151], v248 offset0:136 offset1:138
	ds_read2_b64 v[152:155], v249 offset0:200 offset1:202
	ds_read2_b64 v[156:159], v248 offset0:140 offset1:142
	ds_read2_b64 v[160:163], v249 offset0:204 offset1:206
	s_nop 8
	v_max3_f32 v0, v96, s5, v97
	v_max3_f32 v0, v0, v98, v99
	v_max3_f32 v0, v0, v100, v101
	v_max3_f32 v0, v0, v102, v103
	v_max3_f32 v0, v0, v104, v105
	v_max3_f32 v0, v0, v106, v107
	s_waitcnt lgkmcnt(8)
	v_mfma_f32_32x32x16_bf16 v[80:95], v[4:7], v[116:119], v[80:95]
	v_max3_f32 v0, v0, v108, v109
	v_max3_f32 v0, v0, v110, v111
	s_nop 9
	v_max3_f32 v0, v0, v80, v81
	v_max3_f32 v0, v0, v82, v83
	v_max3_f32 v0, v0, v84, v85
	v_max3_f32 v0, v0, v86, v87
	v_max3_f32 v0, v0, v88, v89
	v_max3_f32 v0, v0, v90, v91
	v_max3_f32 v0, v0, v92, v93
	v_max3_f32 v0, v0, v94, v95
	v_mul_f32_e32 v0, 0x3e8293ee, v0
	v_mov_b32_e32 v3, v0
	s_nop 1
	v_permlane32_swap_b32_e32 v3, v0
	s_nop 0
	v_max3_f32 v0, v2, v0, v3
	v_sub_f32_e32 v3, v2, v0
	v_exp_f32_e32 v14, v3
	v_cmp_neq_f32_e32 vcc, v0, v2
	s_cbranch_vccz .LBB0_433
	v_pk_mul_f32 v[62:63], v[62:63], v[14:15] op_sel_hi:[1,0]
	v_pk_mul_f32 v[60:61], v[60:61], v[14:15] op_sel_hi:[1,0]
	v_pk_mul_f32 v[58:59], v[58:59], v[14:15] op_sel_hi:[1,0]
	v_pk_mul_f32 v[56:57], v[56:57], v[14:15] op_sel_hi:[1,0]
	v_pk_mul_f32 v[54:55], v[54:55], v[14:15] op_sel_hi:[1,0]
	v_pk_mul_f32 v[52:53], v[52:53], v[14:15] op_sel_hi:[1,0]
	v_pk_mul_f32 v[50:51], v[50:51], v[14:15] op_sel_hi:[1,0]
	v_pk_mul_f32 v[48:49], v[48:49], v[14:15] op_sel_hi:[1,0]
	v_pk_mul_f32 v[30:31], v[30:31], v[14:15] op_sel_hi:[1,0]
	v_pk_mul_f32 v[28:29], v[28:29], v[14:15] op_sel_hi:[1,0]
	v_pk_mul_f32 v[26:27], v[26:27], v[14:15] op_sel_hi:[1,0]
	v_pk_mul_f32 v[24:25], v[24:25], v[14:15] op_sel_hi:[1,0]
	v_pk_mul_f32 v[22:23], v[22:23], v[14:15] op_sel_hi:[1,0]
	v_pk_mul_f32 v[20:21], v[20:21], v[14:15] op_sel_hi:[1,0]
	v_pk_mul_f32 v[18:19], v[18:19], v[14:15] op_sel_hi:[1,0]
	v_pk_mul_f32 v[16:17], v[16:17], v[14:15] op_sel_hi:[1,0]
.LBB0_433:
	v_pk_fma_f32 v[2:3], v[96:97], s[58:59], v[0:1] op_sel_hi:[1,0,0] neg_lo:[0,0,1] neg_hi:[0,0,1]
	v_pk_fma_f32 v[4:5], v[98:99], s[58:59], v[0:1] op_sel_hi:[1,0,0] neg_lo:[0,0,1] neg_hi:[0,0,1]
	v_exp_f32_e32 v180, v2
	v_exp_f32_e32 v181, v3
	v_add3_u32 v10, s4, v235, v171
	v_pk_fma_f32 v[2:3], v[100:101], s[58:59], v[0:1] op_sel_hi:[1,0,0] neg_lo:[0,0,1] neg_hi:[0,0,1]
	v_exp_f32_e32 v178, v4
	v_exp_f32_e32 v179, v5
	s_mov_b32 s4, 0xff800000
	v_pk_fma_f32 v[4:5], v[102:103], s[58:59], v[0:1] op_sel_hi:[1,0,0] neg_lo:[0,0,1] neg_hi:[0,0,1]
	v_exp_f32_e32 v182, v2
	v_exp_f32_e32 v183, v3
	v_pk_fma_f32 v[2:3], v[104:105], s[58:59], v[0:1] op_sel_hi:[1,0,0] neg_lo:[0,0,1] neg_hi:[0,0,1]
	v_exp_f32_e32 v184, v4
	v_exp_f32_e32 v185, v5
	v_pk_fma_f32 v[4:5], v[106:107], s[58:59], v[0:1] op_sel_hi:[1,0,0] neg_lo:[0,0,1] neg_hi:[0,0,1]
	v_exp_f32_e32 v186, v2
	v_exp_f32_e32 v187, v3
	v_pk_fma_f32 v[2:3], v[108:109], s[58:59], v[0:1] op_sel_hi:[1,0,0] neg_lo:[0,0,1] neg_hi:[0,0,1]
	v_exp_f32_e32 v188, v4
	v_exp_f32_e32 v189, v5
	v_pk_fma_f32 v[4:5], v[110:111], s[58:59], v[0:1] op_sel_hi:[1,0,0] neg_lo:[0,0,1] neg_hi:[0,0,1]
	v_exp_f32_e32 v194, v2
	v_exp_f32_e32 v195, v3
	v_pk_fma_f32 v[2:3], v[80:81], s[58:59], v[0:1] op_sel_hi:[1,0,0] neg_lo:[0,0,1] neg_hi:[0,0,1]
	v_exp_f32_e32 v200, v4
	v_exp_f32_e32 v201, v5
	v_pk_fma_f32 v[4:5], v[82:83], s[58:59], v[0:1] op_sel_hi:[1,0,0] neg_lo:[0,0,1] neg_hi:[0,0,1]
	v_exp_f32_e32 v198, v2
	v_exp_f32_e32 v199, v3
	v_cvt_pk_bf16_f32 v80, v180, v181
	v_pk_fma_f32 v[2:3], v[84:85], s[58:59], v[0:1] op_sel_hi:[1,0,0] neg_lo:[0,0,1] neg_hi:[0,0,1]
	v_exp_f32_e32 v204, v4
	v_exp_f32_e32 v205, v5
	v_cvt_pk_bf16_f32 v81, v178, v179
	v_pk_fma_f32 v[4:5], v[86:87], s[58:59], v[0:1] op_sel_hi:[1,0,0] neg_lo:[0,0,1] neg_hi:[0,0,1]
	v_exp_f32_e32 v208, v2
	v_exp_f32_e32 v209, v3
	v_add_u32_e32 v84, 0x2000, v10
	v_pk_fma_f32 v[2:3], v[88:89], s[58:59], v[0:1] op_sel_hi:[1,0,0] neg_lo:[0,0,1] neg_hi:[0,0,1]
	v_exp_f32_e32 v190, v4
	v_exp_f32_e32 v191, v5
	v_add_u32_e32 v85, 0x3000, v10
	v_pk_fma_f32 v[4:5], v[90:91], s[58:59], v[0:1] op_sel_hi:[1,0,0] neg_lo:[0,0,1] neg_hi:[0,0,1]
	v_exp_f32_e32 v192, v2
	v_exp_f32_e32 v193, v3
	v_cvt_pk_bf16_f32 v82, v182, v183
	v_pk_fma_f32 v[2:3], v[92:93], s[58:59], v[0:1] op_sel_hi:[1,0,0] neg_lo:[0,0,1] neg_hi:[0,0,1]
	v_exp_f32_e32 v196, v4
	v_exp_f32_e32 v197, v5
	v_cvt_pk_bf16_f32 v83, v184, v185
	v_pk_fma_f32 v[4:5], v[94:95], s[58:59], v[0:1] op_sel_hi:[1,0,0] neg_lo:[0,0,1] neg_hi:[0,0,1]
	v_exp_f32_e32 v202, v2
	v_exp_f32_e32 v203, v3
	s_nop 0
	v_exp_f32_e32 v206, v4
	v_exp_f32_e32 v207, v5
	ds_read2_b64 v[6:9], v84 offset0:128 offset1:130
	ds_read2_b64 v[2:5], v84 offset0:132 offset1:134
	ds_read2_b64 v[10:13], v85 offset0:192 offset1:194
	s_waitcnt lgkmcnt(2)
	v_mfma_f32_32x32x16_bf16 v[48:63], v[6:9], v[80:83], v[48:63]
	s_waitcnt lgkmcnt(0)
	v_mfma_f32_32x32x16_bf16 v[16:31], v[10:13], v[80:83], v[16:31]
	v_cvt_pk_bf16_f32 v80, v186, v187
	v_cvt_pk_bf16_f32 v81, v188, v189
	v_cvt_pk_bf16_f32 v82, v194, v195
	v_cvt_pk_bf16_f32 v83, v200, v201
	s_nop 1
	v_mfma_f32_32x32x16_bf16 v[48:63], v[2:5], v[80:83], v[48:63]
	s_waitcnt lgkmcnt(4)
	v_mfma_f32_32x32x16_bf16 v[16:31], v[144:147], v[80:83], v[16:31]
	v_cvt_pk_bf16_f32 v80, v198, v199
	v_cvt_pk_bf16_f32 v81, v204, v205
	v_cvt_pk_bf16_f32 v82, v208, v209
	v_cvt_pk_bf16_f32 v83, v190, v191
	s_waitcnt lgkmcnt(3)
	s_nop 0
	v_mfma_f32_32x32x16_bf16 v[48:63], v[148:151], v[80:83], v[48:63]
	s_waitcnt lgkmcnt(2)
	v_mfma_f32_32x32x16_bf16 v[16:31], v[152:155], v[80:83], v[16:31]
	v_cvt_pk_bf16_f32 v80, v192, v193
	v_cvt_pk_bf16_f32 v81, v196, v197
	v_cvt_pk_bf16_f32 v82, v202, v203
	v_cvt_pk_bf16_f32 v83, v206, v207
	s_waitcnt lgkmcnt(1)
	s_nop 0
	v_mfma_f32_32x32x16_bf16 v[48:63], v[156:159], v[80:83], v[48:63]
	s_waitcnt lgkmcnt(0)
	v_mfma_f32_32x32x16_bf16 v[16:31], v[160:163], v[80:83], v[16:31]
	ds_read_b128 v[238:241], v210 offset:4704
	v_mfma_f32_32x32x16_bf16 v[96:111], v[244:247], v[120:123], 0
	v_mfma_f32_32x32x16_bf16 v[96:111], v[214:217], v[124:127], v[96:111]
	v_mfma_f32_32x32x16_bf16 v[80:95], v[228:231], v[120:123], 0
	s_nop 10
	v_max3_f32 v210, v96, s4, v97
	v_max3_f32 v210, v210, v98, v99
	v_max3_f32 v210, v210, v100, v101
	v_max3_f32 v210, v210, v102, v103
	v_max3_f32 v210, v210, v104, v105
	v_max3_f32 v210, v210, v106, v107
	v_max3_f32 v210, v210, v108, v109
	s_waitcnt lgkmcnt(0)
	v_mfma_f32_32x32x16_bf16 v[80:95], v[238:241], v[124:127], v[80:95]
	v_max3_f32 v210, v210, v110, v111
	s_nop 10
	v_max3_f32 v210, v210, v80, v81
	v_max3_f32 v210, v210, v82, v83
	v_max3_f32 v210, v210, v84, v85
	v_max3_f32 v210, v210, v86, v87
	v_max3_f32 v210, v210, v88, v89
	v_max3_f32 v210, v210, v90, v91
	v_max3_f32 v210, v210, v92, v93
	v_max3_f32 v210, v210, v94, v95
	v_mul_f32_e32 v210, 0x3e8293ee, v210
	v_mov_b32_e32 v211, v210
	s_nop 1
	v_permlane32_swap_b32_e32 v211, v210
	s_nop 0
	v_max3_f32 v210, v237, v210, v211
	v_sub_f32_e32 v211, v237, v210
	v_exp_f32_e32 v212, v211
	v_cmp_neq_f32_e32 vcc, v210, v237
	s_cbranch_vccz .LBB0_435
	v_pk_mul_f32 v[78:79], v[78:79], v[212:213] op_sel_hi:[1,0]
	v_pk_mul_f32 v[76:77], v[76:77], v[212:213] op_sel_hi:[1,0]
	v_pk_mul_f32 v[74:75], v[74:75], v[212:213] op_sel_hi:[1,0]
	v_pk_mul_f32 v[72:73], v[72:73], v[212:213] op_sel_hi:[1,0]
	v_pk_mul_f32 v[70:71], v[70:71], v[212:213] op_sel_hi:[1,0]
	v_pk_mul_f32 v[68:69], v[68:69], v[212:213] op_sel_hi:[1,0]
	v_pk_mul_f32 v[66:67], v[66:67], v[212:213] op_sel_hi:[1,0]
	v_pk_mul_f32 v[64:65], v[64:65], v[212:213] op_sel_hi:[1,0]
	v_pk_mul_f32 v[46:47], v[46:47], v[212:213] op_sel_hi:[1,0]
	v_pk_mul_f32 v[44:45], v[44:45], v[212:213] op_sel_hi:[1,0]
	v_pk_mul_f32 v[42:43], v[42:43], v[212:213] op_sel_hi:[1,0]
	v_pk_mul_f32 v[40:41], v[40:41], v[212:213] op_sel_hi:[1,0]
	v_pk_mul_f32 v[38:39], v[38:39], v[212:213] op_sel_hi:[1,0]
	v_pk_mul_f32 v[36:37], v[36:37], v[212:213] op_sel_hi:[1,0]
	v_pk_mul_f32 v[34:35], v[34:35], v[212:213] op_sel_hi:[1,0]
	v_pk_mul_f32 v[32:33], v[32:33], v[212:213] op_sel_hi:[1,0]
